# v034_ssm2
# speedup vs baseline: 1.0131x; 1.0131x over previous
; #define SCHED __builtin_amdgcn_sched_barrier(0)
; __device__ __forceinline__ void ssm_item(const Params& p, int layer, int item, const int tidx) {
;     ...
;       for (int s0 = kh * 32; s0 < kh * 32 + 32; s0 += 16) {
;         u32x4 ea[16];
; #pragma unroll
;         for (int j = 0; j < 16; ++j) ea[j] = *reinterpret_cast<const u32x4*>(E + ((size_t)(rt * 64 + s0 + j) * 64 + lane) * 8);
;         SCHED;
; #pragma unroll
;         for (int j = 0; j < 16; ++j) {
;           u32x4 bb = *reinterpret_cast<const u32x4*>(U + n * USTR + (s0 + j) * 32 + half * 16);
;           acc = __builtin_amdgcn_mfma_f32_32x32x16_bf16(as_bf16x8(ea[j]), as_bf16x8(bb), acc, 0, 0, 0);
;         }
;       }
; #pragma unroll
;       for (int rg = 0; rg < 4; ++rg) {
;         f32x4 o = {acc[rg * 4 + 0], acc[rg * 4 + 1], acc[rg * 4 + 2], acc[rg * 4 + 3]};
;         *reinterpret_cast<f32x4*>(S + (kh * 32 + n) * 128 + rt * 32 + 8 * rg + 4 * half) = o;
;       }
;     }
;     __syncthreads();
;     if (tid < 64) {
; #pragma unroll 1
;       for (int c0 = 0; c0 < 32; c0 += 8) {
;         float sr[8], si[8];
; #pragma unroll
;         for (int c = 0; c < 8; ++c) {
;           sr[c] = S[(c0 + c) * 128 + tid] + S[(32 + c0 + c) * 128 + tid];
;           si[c] = S[(c0 + c) * 128 + 64 + tid] + S[(32 + c0 + c) * 128 + 64 + tid];
;         }
; #pragma unroll
;         for (int c = 0; c < 8; ++c) {
;           *reinterpret_cast<u16*>(XIN + (c0 + c) * XSTR + tid * 2) = f2bf(xre);
;           *reinterpret_cast<u16*>(XIN + (c0 + c) * XSTR + (64 + tid) * 2) = f2bf(xim);
;           float nr = lre * xre - lim * xim + sr[c], ni = lre * xim + lim * xre + si[c];
;           xre = nr;
;           xim = ni;
;         }
;       }
;     }
;     __syncthreads();
;     {
;       char* KML = (char*)S;
; #pragma unroll
;       for (int i = 0; i < 4; ++i) {
;         int idx = i * NTHR + tid;
;         *reinterpret_cast<u32x4*>(KML + idx * 16) = *reinterpret_cast<const u32x4*>(KM + (size_t)idx * 8);
;       }
;     }
;     __syncthreads();
;     {
;       const char* KML = (const char*)S;
; #pragma unroll 1
;       for (int i = 0; i < 4; ++i) {
;         int rt = wid + 8 * i, t0l = 2 * rt;
;         int tA = t0l + (n >> 4), co = n & 15;
;         u32x4 fa[8];
; #pragma unroll
;         for (int ks = 0; ks < 8; ++ks) fa[ks] = *reinterpret_cast<const u32x4*>(F + ((size_t)(rt * 8 + ks) * 64 + lane) * 8);
.LBB0_205:
	s_movk_i32 s15, 0xd000
	v_add_co_u32_e32 v52, vcc, s15, v24
	s_movk_i32 s15, 0xf000
	s_nop 0
	v_addc_co_u32_e32 v53, vcc, -1, v25, vcc
	v_add_co_u32_e32 v68, vcc, s62, v24
	global_load_dwordx4 v[28:31], v[52:53], off offset:-3072
	global_load_dwordx4 v[32:35], v[52:53], off offset:-2048
	v_addc_co_u32_e32 v69, vcc, -1, v25, vcc
	v_add_co_u32_e32 v64, vcc, s15, v24
	global_load_dwordx4 v[36:39], v[68:69], off offset:-4096
	global_load_dwordx4 v[40:43], v[68:69], off offset:-3072
	global_load_dwordx4 v[44:47], v[68:69], off offset:-2048
	global_load_dwordx4 v[48:51], v[68:69], off offset:-1024
	v_addc_co_u32_e32 v65, vcc, -1, v25, vcc
	global_load_dwordx4 v[52:55], v[52:53], off offset:-1024
	s_nop 0
	global_load_dwordx4 v[56:59], v[64:65], off offset:-3072
	global_load_dwordx4 v[60:63], v[64:65], off offset:-2048
	s_nop 0
	global_load_dwordx4 v[64:67], v[64:65], off offset:-1024
	s_nop 0
	global_load_dwordx4 v[68:71], v[68:69], off
	s_nop 0
	global_load_dwordx4 v[72:75], v[24:25], off offset:-4096
	global_load_dwordx4 v[76:79], v[24:25], off offset:-3072
	global_load_dwordx4 v[80:83], v[24:25], off offset:-2048
	global_load_dwordx4 v[84:87], v[24:25], off offset:-1024
	global_load_dwordx4 v[88:91], v[24:25], off
	ds_read_b128 v[152:155], v26
	v_add_u32_e32 v27, 16, v27
	v_cmp_gt_i32_e32 vcc, v27, v115
	s_or_b64 s[12:13], vcc, s[12:13]
	v_lshl_add_u64 v[24:25], v[24:25], 0, s[40:41]
	s_waitcnt vmcnt(15) lgkmcnt(0)
	v_mfma_f32_32x32x16_bf16 v[0:15], v[28:31], v[152:155], v[0:15]
	ds_read_b128 v[28:31], v26 offset:32
	s_waitcnt vmcnt(14) lgkmcnt(0)
	v_mfma_f32_32x32x16_bf16 v[0:15], v[32:35], v[28:31], v[0:15]
	ds_read_b128 v[28:31], v26 offset:64
	s_waitcnt vmcnt(9) lgkmcnt(0)
	v_mfma_f32_32x32x16_bf16 v[0:15], v[52:55], v[28:31], v[0:15]
	ds_read_b128 v[28:31], v26 offset:96
	s_waitcnt lgkmcnt(0)
	v_mfma_f32_32x32x16_bf16 v[0:15], v[36:39], v[28:31], v[0:15]
	ds_read_b128 v[28:31], v26 offset:128
	s_waitcnt lgkmcnt(0)
	v_mfma_f32_32x32x16_bf16 v[0:15], v[40:43], v[28:31], v[0:15]
	ds_read_b128 v[28:31], v26 offset:160
	s_waitcnt lgkmcnt(0)
	v_mfma_f32_32x32x16_bf16 v[0:15], v[44:47], v[28:31], v[0:15]
	ds_read_b128 v[28:31], v26 offset:192
	s_waitcnt lgkmcnt(0)
	v_mfma_f32_32x32x16_bf16 v[0:15], v[48:51], v[28:31], v[0:15]
	ds_read_b128 v[28:31], v26 offset:224
	s_waitcnt vmcnt(5) lgkmcnt(0)
	v_mfma_f32_32x32x16_bf16 v[0:15], v[68:71], v[28:31], v[0:15]
	ds_read_b128 v[28:31], v26 offset:256
	s_waitcnt lgkmcnt(0)
	v_mfma_f32_32x32x16_bf16 v[0:15], v[56:59], v[28:31], v[0:15]
	ds_read_b128 v[28:31], v26 offset:288
	s_waitcnt lgkmcnt(0)
	v_mfma_f32_32x32x16_bf16 v[0:15], v[60:63], v[28:31], v[0:15]
	ds_read_b128 v[28:31], v26 offset:320
	s_waitcnt lgkmcnt(0)
	v_mfma_f32_32x32x16_bf16 v[0:15], v[64:67], v[28:31], v[0:15]
	ds_read_b128 v[28:31], v26 offset:352
	s_waitcnt vmcnt(4) lgkmcnt(0)
	v_mfma_f32_32x32x16_bf16 v[0:15], v[72:75], v[28:31], v[0:15]
	ds_read_b128 v[28:31], v26 offset:384
	s_waitcnt vmcnt(3) lgkmcnt(0)
	v_mfma_f32_32x32x16_bf16 v[0:15], v[76:79], v[28:31], v[0:15]
	ds_read_b128 v[28:31], v26 offset:416
	s_waitcnt vmcnt(2) lgkmcnt(0)
	v_mfma_f32_32x32x16_bf16 v[0:15], v[80:83], v[28:31], v[0:15]
	ds_read_b128 v[28:31], v26 offset:448
	s_waitcnt vmcnt(1) lgkmcnt(0)
	v_mfma_f32_32x32x16_bf16 v[0:15], v[84:87], v[28:31], v[0:15]
	ds_read_b128 v[28:31], v26 offset:480
	v_add_u32_e32 v26, 0x200, v26
	s_waitcnt vmcnt(0) lgkmcnt(0)
	v_mfma_f32_32x32x16_bf16 v[0:15], v[88:91], v[28:31], v[0:15]
	s_andn2_b64 exec, exec, s[12:13]
	s_cbranch_execnz .LBB0_205
	s_or_b64 exec, exec, s[12:13]
	s_nop 8
	ds_write_b128 v124, v[0:3]
	ds_write_b128 v124, v[4:7] offset:32
	ds_write_b128 v124, v[8:11] offset:64
	ds_write_b128 v124, v[12:15] offset:96
	s_waitcnt lgkmcnt(0)
	s_barrier
	global_load_dwordx4 v[192:195], v[102:103], off
	global_load_dwordx4 v[196:199], v[104:105], off
	global_load_dwordx4 v[200:203], v[106:107], off
	global_load_dwordx4 v[204:207], v[108:109], off
	v_lshlrev_b32_e32 v168, 13, v97
	v_mov_b32_e32 v169, 0
	v_lshl_add_u64 v[168:169], v[100:101], 0, v[168:169]
	v_add_co_u32_e32 v170, vcc, 0x1000, v168
	s_nop 1
	v_addc_co_u32_e32 v171, vcc, 0, v169, vcc
	global_load_dwordx4 v[222:225], v[168:169], off
	global_load_dwordx4 v[226:229], v[168:169], off offset:1024
	global_load_dwordx4 v[230:233], v[168:169], off offset:2048
	global_load_dwordx4 v[234:237], v[168:169], off offset:3072
	global_load_dwordx4 v[238:241], v[170:171], off
	global_load_dwordx4 v[242:245], v[170:171], off offset:1024
	global_load_dwordx4 v[246:249], v[170:171], off offset:2048
	global_load_dwordx4 v[250:253], v[170:171], off offset:3072
	s_and_saveexec_b64 s[12:13], s[6:7]
	s_cbranch_execz .LBB0_209
	s_mov_b32 s15, -8
	v_mov_b32_e32 v26, v137
	v_mov_b32_e32 v27, v92

; __device__ __forceinline__ void ssm_item(const Params& p, int layer, int item, const int tidx) {
;     ...
;       for (int i = 0; i < 4; ++i) {
;         int idx = i * NTHR + tid;
;         *reinterpret_cast<u32x4*>(KML + idx * 16) = *reinterpret_cast<const u32x4*>(KM + (size_t)idx * 8);
;       }
;     }
;     __syncthreads();
;     {
;       const char* KML = (const char*)S;
; #pragma unroll 1
;       for (int i = 0; i < 4; ++i) {
;         int rt = wid + 8 * i, t0l = 2 * rt;
;         int tA = t0l + (n >> 4), co = n & 15;
;         u32x4 fa[8];
; #pragma unroll
;         for (int ks = 0; ks < 8; ++ks) fa[ks] = *reinterpret_cast<const u32x4*>(F + ((size_t)(rt * 8 + ks) * 64 + lane) * 8);
;         f32x16 acc;
; #pragma unroll
;         for (int q = 0; q < 16; ++q) acc[q] = 0.f;
;         const char* ub = U + n * USTR + half * 16;
;         const char* kb = KML + (co * 16 + 8 * half) * 2;
; #pragma unroll 4
;         for (int s = 0; s <= t0l; ++s) {
;           u32x4 a = *reinterpret_cast<const u32x4*>(kb + (tA - s) * 512);
;           u32x4 bb = *reinterpret_cast<const u32x4*>(ub + s * 32);
;           acc = __builtin_amdgcn_mfma_f32_32x32x16_bf16(as_bf16x8(a), as_bf16x8(bb), acc, 0, 0, 0);
;         }
;         {
;           u32x4 a = *reinterpret_cast<const u32x4*>(kb);
;           if (tA == t0l) a = u32x4{0u, 0u, 0u, 0u};
;           u32x4 bb = *reinterpret_cast<const u32x4*>(ub + (t0l + 1) * 32);
;           acc = __builtin_amdgcn_mfma_f32_32x32x16_bf16(as_bf16x8(a), as_bf16x8(bb), acc, 0, 0, 0);
;         }
; #pragma unroll
;         for (int ks = 0; ks < 8; ++ks) {
;           u32x4 bb = *reinterpret_cast<const u32x4*>(XIN + n * XSTR + (ks * 16 + 8 * half) * 2);
;           acc = __builtin_amdgcn_mfma_f32_32x32x16_bf16(as_bf16x8(fa[ks]), as_bf16x8(bb), acc, 0, 0, 0);
;         }
; #pragma unroll
;         for (int rg = 0; rg < 4; ++rg) {
;           int tl = t0l + (rg >> 1), co0 = 8 * (rg & 1) + 4 * half;
;           u32x2 uu = *reinterpret_cast<const u32x2*>(U + n * USTR + tl * 32 + co0 * 2);
;           f32x4 d = dsk[rg & 1];
;           float y0 = acc[rg * 4 + 0] + d[0] * bflo(uu.x);
;           float y1 = acc[rg * 4 + 1] + d[1] * bfhi(uu.x);
;           float y2 = acc[rg * 4 + 2] + d[2] * bflo(uu.y);
;           float y3 = acc[rg * 4 + 3] + d[3] * bfhi(uu.y);
;           u32x2 o;
;           o.x = pack2(geluf_(y0), geluf_(y1));
.LBB0_209:
	s_or_b64 exec, exec, s[12:13]
	s_waitcnt lgkmcnt(0)
	s_barrier
	v_readlane_b32 s12, v254, 16
	v_or_b32_e32 v162, s14, v125
	s_mov_b32 s16, 0
	v_add_u32_e32 v4, s12, v93
	v_mov_b32_e32 v152, v138
	v_mov_b32_e32 v153, v126
	s_waitcnt vmcnt(11)
	ds_write_b128 v4, v[192:195]
	s_waitcnt vmcnt(10)
	ds_write_b128 v149, v[196:199]
	s_waitcnt vmcnt(9)
	ds_write_b128 v150, v[200:203]
	s_waitcnt vmcnt(8)
	ds_write_b128 v151, v[204:207]
	s_waitcnt lgkmcnt(0)
	s_barrier
	ds_read_b128 v[0:3], v147
	ds_read_b128 v[28:31], v148
	ds_read_b128 v[32:35], v148 offset:32
	ds_read_b128 v[36:39], v148 offset:64
	ds_read_b128 v[40:43], v148 offset:96
	ds_read_b128 v[44:47], v148 offset:128
	ds_read_b128 v[48:51], v148 offset:160
	ds_read_b128 v[52:55], v148 offset:192
	ds_read_b128 v[56:59], v148 offset:224
	s_waitcnt lgkmcnt(8)
	v_cndmask_b32_e64 v27, v3, 0, s[8:9]
	v_cndmask_b32_e64 v26, v2, 0, s[8:9]
	v_cndmask_b32_e64 v25, v1, 0, s[8:9]
	v_cndmask_b32_e64 v24, v0, 0, s[8:9]
	s_waitcnt vmcnt(0)
	s_branch .LBB0_211
.LBB0_210:
	s_or_b64 exec, exec, s[12:13]
	v_lshlrev_b32_e32 v155, 6, v154
	v_add_u32_e32 v156, v123, v155
	ds_read_b128 v[156:159], v156 offset:32
	s_add_i32 s16, s16, 1
	v_add_u32_e32 v153, 16, v153
	s_cmp_eq_u32 s16, 4
	v_add_u32_e32 v152, 0x2000, v152
	s_waitcnt lgkmcnt(0)
	v_mfma_f32_32x32x16_bf16 v[0:15], v[24:27], v[156:159], v[0:15]
	v_mfma_f32_32x32x16_bf16 v[0:15], v[72:75], v[28:31], v[0:15]
	v_add_u32_e32 v74, v122, v155
	v_lshlrev_b32_e32 v72, 1, v154
	v_ashrrev_i32_e32 v73, 31, v72
	v_mfma_f32_32x32x16_bf16 v[0:15], v[76:79], v[32:35], v[0:15]
	v_mfma_f32_32x32x16_bf16 v[0:15], v[80:83], v[36:39], v[0:15]
	v_mfma_f32_32x32x16_bf16 v[0:15], v[84:87], v[40:43], v[0:15]
	v_mfma_f32_32x32x16_bf16 v[0:15], v[88:91], v[44:47], v[0:15]
	v_mfma_f32_32x32x16_bf16 v[0:15], v[68:71], v[48:51], v[0:15]
	v_add_u32_e32 v70, v74, v110
	ds_read_b64 v[70:71], v70
	v_lshl_add_u64 v[68:69], v[72:73], 0, v[162:163]
	v_add_u32_e32 v73, v74, v135
	ds_read_b64 v[74:75], v73
	v_lshlrev_b64 v[68:69], 11, v[68:69]
	v_lshl_add_u64 v[68:69], v[116:117], 0, v[68:69]
	v_mfma_f32_32x32x16_bf16 v[0:15], v[64:67], v[52:55], v[0:15]
	s_waitcnt lgkmcnt(1)
	v_lshlrev_b32_e32 v64, 16, v70
	v_and_b32_e32 v65, 0xffff0000, v70
	v_lshlrev_b32_e32 v66, 16, v71
	v_and_b32_e32 v67, 0xffff0000, v71
	s_waitcnt lgkmcnt(0)
	v_lshlrev_b32_e32 v70, 16, v74
	v_and_b32_e32 v71, 0xffff0000, v74
	v_lshlrev_b32_e32 v73, 16, v75
	v_mfma_f32_32x32x16_bf16 v[0:15], v[60:63], v[56:59], v[0:15]
	s_nop 11
	v_fma_f32 v0, v16, v64, v0
	v_fma_f32 v1, v17, v65, v1
	v_fma_f32 v2, v18, v66, v2
	v_fma_f32 v3, v19, v67, v3
	v_mul_f32_e32 v60, 0x3d372713, v0
	v_mul_f32_e32 v62, 0x3d372713, v1
	v_mul_f32_e32 v64, 0x3d372713, v2
	v_mul_f32_e32 v66, 0x3d372713, v3
	v_mul_f32_e32 v60, v0, v60
	v_mul_f32_e32 v62, v1, v62
	v_mul_f32_e32 v64, v2, v64
	v_mul_f32_e32 v61, 0.5, v0
	v_mul_f32_e32 v63, 0.5, v1
	v_mul_f32_e32 v65, 0.5, v2
	v_mul_f32_e32 v66, v3, v66
	v_fma_f32 v0, v0, v60, v0
	v_fma_f32 v1, v1, v62, v1
	v_fma_f32 v2, v2, v64, v2
	v_fma_f32 v4, v20, v70, v4
	v_mul_f32_e32 v67, 0.5, v3
	v_fma_f32 v3, v3, v66, v3
	v_mul_f32_e32 v0, 0x3f4c422a, v0
	v_mul_f32_e32 v1, 0x3f4c422a, v1
	v_mul_f32_e32 v2, 0x3f4c422a, v2
	v_mul_f32_e32 v70, 0x3d372713, v4
	v_mul_f32_e32 v3, 0x3f4c422a, v3
	v_add_f32_e32 v0, v0, v0
	v_add_f32_e32 v1, v1, v1
	v_add_f32_e32 v2, v2, v2
	v_mul_f32_e32 v70, v4, v70
	v_add_f32_e32 v3, v3, v3
	v_mul_f32_e32 v0, 0x3fb8aa3b, v0
	v_mul_f32_e32 v1, 0x3fb8aa3b, v1
	v_mul_f32_e32 v2, 0x3fb8aa3b, v2
	v_fma_f32 v60, v4, v70, v4
	v_mul_f32_e32 v3, 0x3fb8aa3b, v3
	v_exp_f32_e32 v0, v0
	v_exp_f32_e32 v1, v1
	v_exp_f32_e32 v2, v2
	v_mul_f32_e32 v60, 0x3f4c422a, v60
	v_exp_f32_e32 v3, v3
	v_add_f32_e32 v60, v60, v60
	v_mul_f32_e32 v60, 0x3fb8aa3b, v60
	v_exp_f32_e32 v60, v60
	v_add_f32_e32 v0, 1.0, v0
	v_add_f32_e32 v1, 1.0, v1
	v_add_f32_e32 v2, 1.0, v2
	v_add_f32_e32 v3, 1.0, v3
	v_rcp_f32_e32 v0, v0
	v_rcp_f32_e32 v1, v1
	v_rcp_f32_e32 v2, v2
	v_rcp_f32_e32 v3, v3
	v_add_f32_e32 v60, 1.0, v60
	v_rcp_f32_e32 v60, v60
	v_fma_f32 v0, v0, -2.0, 1.0
	v_fma_f32 v1, v1, -2.0, 1.0
	v_fma_f32 v2, v2, -2.0, 1.0
	v_fma_f32 v3, v3, -2.0, 1.0
	v_add_f32_e32 v0, 1.0, v0
	v_add_f32_e32 v1, 1.0, v1
	v_add_f32_e32 v2, 1.0, v2
	v_fma_f32 v5, v21, v71, v5
	v_add_f32_e32 v3, 1.0, v3
	v_mul_f32_e32 v0, v61, v0
	v_mul_f32_e32 v1, v63, v1
	v_mul_f32_e32 v2, v65, v2
	v_mul_f32_e32 v3, v67, v3
	v_cvt_pk_bf16_f32 v0, v0, v1
	v_cvt_pk_bf16_f32 v1, v2, v3
	v_mul_f32_e32 v2, 0x3d372713, v5
	global_store_dwordx2 v[68:69], v[0:1], off
	v_fma_f32 v1, v60, -2.0, 1.0
	v_mul_f32_e32 v2, v5, v2
	v_fma_f32 v6, v22, v73, v6
	v_fma_f32 v2, v5, v2, v5
	v_mul_f32_e32 v3, 0.5, v4
	v_add_f32_e32 v1, 1.0, v1
	v_mul_f32_e32 v2, 0x3f4c422a, v2
	v_mul_f32_e32 v1, v3, v1
	v_mul_f32_e32 v3, 0x3d372713, v6
	v_add_f32_e32 v2, v2, v2
	v_mul_f32_e32 v3, v6, v3
	v_mul_f32_e32 v2, 0x3fb8aa3b, v2
	v_fma_f32 v3, v6, v3, v6
	v_and_b32_e32 v0, 0xffff0000, v75
	v_exp_f32_e32 v2, v2
	v_mul_f32_e32 v3, 0x3f4c422a, v3
	v_fma_f32 v0, v23, v0, v7
	v_add_f32_e32 v3, v3, v3
	v_mul_f32_e32 v3, 0x3fb8aa3b, v3
	v_mul_f32_e32 v4, 0.5, v5
	v_mul_f32_e32 v5, 0x3d372713, v0
	v_exp_f32_e32 v3, v3
	v_mul_f32_e32 v5, v0, v5
	v_add_f32_e32 v2, 1.0, v2
	v_fma_f32 v5, v0, v5, v0
	v_rcp_f32_e32 v2, v2
	v_mul_f32_e32 v5, 0x3f4c422a, v5
	v_add_f32_e32 v5, v5, v5
	v_add_f32_e32 v3, 1.0, v3
	v_mul_f32_e32 v5, 0x3fb8aa3b, v5
	v_rcp_f32_e32 v3, v3
	v_exp_f32_e32 v5, v5
	v_fma_f32 v2, v2, -2.0, 1.0
	v_add_f32_e32 v2, 1.0, v2
	v_mul_f32_e32 v2, v4, v2
	v_cvt_pk_bf16_f32 v2, v1, v2
	v_fma_f32 v1, v3, -2.0, 1.0
	v_add_f32_e32 v3, 1.0, v5
	v_mul_f32_e32 v4, 0.5, v6
	v_mul_f32_e32 v6, 0.5, v0
	v_or_b32_e32 v0, 1, v72
	v_rcp_f32_e32 v3, v3
	v_add_f32_e32 v1, 1.0, v1
	v_lshl_add_u32 v7, v0, 5, v122
	v_mul_f32_e32 v1, v4, v1
	v_add_u32_e32 v4, v7, v110
	ds_read_b64 v[4:5], v4
	v_fma_f32 v3, v3, -2.0, 1.0
	v_add_f32_e32 v3, 1.0, v3
	v_mul_f32_e32 v3, v6, v3
	v_cvt_pk_bf16_f32 v3, v1, v3
	s_waitcnt lgkmcnt(0)
; __device__ __forceinline__ float bflo(unsigned u) { return __uint_as_float(u << 16); }
; __device__ __forceinline__ void ssm_item(const Params& p, int layer, int item, const int tidx) {
;     ...
;         int rt = wid + 8 * i, t0l = 2 * rt;
;         int tA = t0l + (n >> 4), co = n & 15;
;         u32x4 fa[8];
; #pragma unroll
;         for (int ks = 0; ks < 8; ++ks) fa[ks] = *reinterpret_cast<const u32x4*>(F + ((size_t)(rt * 8 + ks) * 64 + lane) * 8);
;         f32x16 acc;
; #pragma unroll
;         for (int q = 0; q < 16; ++q) acc[q] = 0.f;
;         const char* ub = U + n * USTR + half * 16;
;         const char* kb = KML + (co * 16 + 8 * half) * 2;
; #pragma unroll 4
;         for (int s = 0; s <= t0l; ++s) {
;           u32x4 a = *reinterpret_cast<const u32x4*>(kb + (tA - s) * 512);
;           u32x4 bb = *reinterpret_cast<const u32x4*>(ub + s * 32);
;           acc = __builtin_amdgcn_mfma_f32_32x32x16_bf16(as_bf16x8(a), as_bf16x8(bb), acc, 0, 0, 0);
;         }
;         {
;           u32x4 a = *reinterpret_cast<const u32x4*>(kb);
;           if (tA == t0l) a = u32x4{0u, 0u, 0u, 0u};
;           u32x4 bb = *reinterpret_cast<const u32x4*>(ub + (t0l + 1) * 32);
;           acc = __builtin_amdgcn_mfma_f32_32x32x16_bf16(as_bf16x8(a), as_bf16x8(bb), acc, 0, 0, 0);
;         }
; #pragma unroll
;         for (int ks = 0; ks < 8; ++ks) {
;           u32x4 bb = *reinterpret_cast<const u32x4*>(XIN + n * XSTR + (ks * 16 + 8 * half) * 2);
;           acc = __builtin_amdgcn_mfma_f32_32x32x16_bf16(as_bf16x8(fa[ks]), as_bf16x8(bb), acc, 0, 0, 0);
;         }
; #pragma unroll
;         for (int rg = 0; rg < 4; ++rg) {
;           int tl = t0l + (rg >> 1), co0 = 8 * (rg & 1) + 4 * half;
;           u32x2 uu = *reinterpret_cast<const u32x2*>(U + n * USTR + tl * 32 + co0 * 2);
;           f32x4 d = dsk[rg & 1];
;           float y0 = acc[rg * 4 + 0] + d[0] * bflo(uu.x);
;           float y1 = acc[rg * 4 + 1] + d[1] * bfhi(uu.x);
;           float y2 = acc[rg * 4 + 2] + d[2] * bflo(uu.y);
;           float y3 = acc[rg * 4 + 3] + d[3] * bfhi(uu.y);
;           u32x2 o;
;           o.x = pack2(geluf_(y0), geluf_(y1));
;           o.y = pack2(geluf_(y2), geluf_(y3));
;           size_t tok = (size_t)b * SEQ + (hf * 32 + n) * 64 + tl;
;           *reinterpret_cast<u32x2*>(hs + tok * 1024 + g * 16 + co0) = o;
;         }
	v_lshlrev_b32_e32 v1, 16, v4
	v_fma_f32 v1, v16, v1, v8
	global_store_dwordx2 v[68:69], v[2:3], off offset:16
	v_mul_f32_e32 v2, 0x3d372713, v1
	v_mul_f32_e32 v2, v1, v2
	v_fma_f32 v2, v1, v2, v1
	v_mul_f32_e32 v2, 0x3f4c422a, v2
	v_add_f32_e32 v2, v2, v2
	v_mul_f32_e32 v2, 0x3fb8aa3b, v2
	v_and_b32_e32 v3, 0xffff0000, v4
	v_exp_f32_e32 v2, v2
	v_fma_f32 v3, v17, v3, v9
	v_mul_f32_e32 v6, 0x3d372713, v3
	v_mul_f32_e32 v6, v3, v6
	v_fma_f32 v6, v3, v6, v3
	v_add_f32_e32 v2, 1.0, v2
	v_mul_f32_e32 v6, 0x3f4c422a, v6
	v_rcp_f32_e32 v2, v2
	v_add_f32_e32 v6, v6, v6
	v_mul_f32_e32 v6, 0x3fb8aa3b, v6
	v_exp_f32_e32 v6, v6
	v_lshlrev_b32_e32 v4, 16, v5
	v_fma_f32 v2, v2, -2.0, 1.0
	v_fma_f32 v4, v18, v4, v10
	v_and_b32_e32 v5, 0xffff0000, v5
	v_mul_f32_e32 v1, 0.5, v1
	v_add_f32_e32 v2, 1.0, v2
	v_fma_f32 v5, v19, v5, v11
	v_mul_f32_e32 v1, v1, v2
	v_add_f32_e32 v2, 1.0, v6
	v_mul_f32_e32 v6, 0x3d372713, v4
	v_mul_f32_e32 v6, v4, v6
	v_mul_f32_e32 v8, 0x3d372713, v5
	v_fma_f32 v6, v4, v6, v4
	v_mul_f32_e32 v8, v5, v8
	v_mul_f32_e32 v6, 0x3f4c422a, v6
	v_fma_f32 v8, v5, v8, v5
	v_add_f32_e32 v6, v6, v6
	v_mul_f32_e32 v8, 0x3f4c422a, v8
	v_rcp_f32_e32 v2, v2
	v_mul_f32_e32 v6, 0x3fb8aa3b, v6
	v_add_f32_e32 v8, v8, v8
	v_exp_f32_e32 v6, v6
	v_mul_f32_e32 v8, 0x3fb8aa3b, v8
	v_exp_f32_e32 v8, v8
	v_fma_f32 v2, v2, -2.0, 1.0
	v_mul_f32_e32 v3, 0.5, v3
	v_add_f32_e32 v2, 1.0, v2
	v_add_f32_e32 v6, 1.0, v6
	v_rcp_f32_e32 v6, v6
	v_mul_f32_e32 v2, v3, v2
	v_add_f32_e32 v3, 1.0, v8
	v_rcp_f32_e32 v3, v3
	v_cvt_pk_bf16_f32 v2, v1, v2
	v_fma_f32 v1, v6, -2.0, 1.0
	v_mul_f32_e32 v4, 0.5, v4
	v_add_f32_e32 v1, 1.0, v1
	v_fma_f32 v3, v3, -2.0, 1.0
	v_mul_f32_e32 v1, v4, v1
	v_mul_f32_e32 v4, 0.5, v5
	v_add_f32_e32 v3, 1.0, v3
	v_mul_f32_e32 v3, v4, v3
	v_add_u32_e32 v4, v7, v135
	ds_read_b64 v[4:5], v4
	v_cvt_pk_bf16_f32 v3, v1, v3
	v_ashrrev_i32_e32 v1, 31, v0
	v_lshl_add_u64 v[0:1], v[0:1], 0, v[162:163]
	v_lshlrev_b64 v[0:1], 11, v[0:1]
	v_lshl_add_u64 v[0:1], v[116:117], 0, v[0:1]
	global_store_dwordx2 v[0:1], v[2:3], off
	s_waitcnt lgkmcnt(0)
	v_lshlrev_b32_e32 v2, 16, v4
	v_fma_f32 v2, v20, v2, v12
	v_mul_f32_e32 v3, 0x3d372713, v2
	v_mul_f32_e32 v3, v2, v3
	v_fma_f32 v3, v2, v3, v2
	v_mul_f32_e32 v3, 0x3f4c422a, v3
	v_add_f32_e32 v3, v3, v3
	v_mul_f32_e32 v3, 0x3fb8aa3b, v3
	v_and_b32_e32 v4, 0xffff0000, v4
	v_exp_f32_e32 v3, v3
	v_fma_f32 v4, v21, v4, v13
	v_lshlrev_b32_e32 v6, 16, v5
	v_and_b32_e32 v5, 0xffff0000, v5
	v_fmac_f32_e32 v15, v23, v5
	v_mul_f32_e32 v5, 0x3d372713, v4
	v_mul_f32_e32 v5, v4, v5
	v_fma_f32 v5, v4, v5, v4
	v_add_f32_e32 v3, 1.0, v3
	v_mul_f32_e32 v5, 0x3f4c422a, v5
	v_rcp_f32_e32 v3, v3
	v_add_f32_e32 v5, v5, v5
	v_mul_f32_e32 v5, 0x3fb8aa3b, v5
	v_exp_f32_e32 v5, v5
	v_fma_f32 v3, v3, -2.0, 1.0
	v_fma_f32 v6, v22, v6, v14
	v_mul_f32_e32 v2, 0.5, v2
	v_add_f32_e32 v3, 1.0, v3
	v_mul_f32_e32 v2, v2, v3
	v_add_f32_e32 v3, 1.0, v5
	v_mul_f32_e32 v5, 0x3d372713, v6
	v_mul_f32_e32 v5, v6, v5
	v_mul_f32_e32 v7, 0x3d372713, v15
	v_fma_f32 v5, v6, v5, v6
	v_mul_f32_e32 v7, v15, v7
	v_mul_f32_e32 v5, 0x3f4c422a, v5
	v_fma_f32 v7, v15, v7, v15
	v_add_f32_e32 v5, v5, v5
	v_mul_f32_e32 v7, 0x3f4c422a, v7
	v_rcp_f32_e32 v3, v3
	v_mul_f32_e32 v5, 0x3fb8aa3b, v5
	v_add_f32_e32 v7, v7, v7
	v_exp_f32_e32 v5, v5
	v_mul_f32_e32 v7, 0x3fb8aa3b, v7
	v_exp_f32_e32 v7, v7
	v_fma_f32 v3, v3, -2.0, 1.0
	v_mul_f32_e32 v4, 0.5, v4
	v_add_f32_e32 v3, 1.0, v3
	v_add_f32_e32 v5, 1.0, v5
	v_rcp_f32_e32 v5, v5
	v_mul_f32_e32 v3, v4, v3
	v_add_f32_e32 v4, 1.0, v7
	v_rcp_f32_e32 v4, v4
	v_cvt_pk_bf16_f32 v2, v2, v3
	v_fma_f32 v3, v5, -2.0, 1.0
	v_mul_f32_e32 v5, 0.5, v6
	v_add_f32_e32 v3, 1.0, v3
	v_fma_f32 v4, v4, -2.0, 1.0
	v_mul_f32_e32 v3, v5, v3
	v_mul_f32_e32 v5, 0.5, v15
	v_add_f32_e32 v4, 1.0, v4
	v_mul_f32_e32 v4, v5, v4
	v_cvt_pk_bf16_f32 v3, v3, v4
	global_store_dwordx2 v[0:1], v[2:3], off offset:16
	s_waitcnt vmcnt(4)
	s_cbranch_scc1 .LBB0_203
.LBB0_211:
	v_lshl_add_u32 v154, s16, 3, v97
	v_mov_b32_e32 v72, v222
	v_mov_b32_e32 v73, v223
	v_mov_b32_e32 v74, v224
	v_mov_b32_e32 v75, v225
	v_mov_b32_e32 v76, v226
	v_mov_b32_e32 v77, v227
	v_mov_b32_e32 v78, v228
	v_mov_b32_e32 v79, v229
	v_mov_b32_e32 v80, v230
	v_mov_b32_e32 v81, v231
	v_mov_b32_e32 v82, v232
	v_mov_b32_e32 v83, v233
	v_mov_b32_e32 v84, v234
	v_mov_b32_e32 v85, v235
	v_mov_b32_e32 v86, v236
	v_mov_b32_e32 v87, v237
	v_mov_b32_e32 v88, v238
	v_mov_b32_e32 v89, v239
	v_mov_b32_e32 v90, v240
	v_mov_b32_e32 v91, v241
	v_mov_b32_e32 v68, v242
	v_mov_b32_e32 v69, v243
	v_mov_b32_e32 v70, v244
	v_mov_b32_e32 v71, v245
	v_mov_b32_e32 v64, v246
	v_mov_b32_e32 v65, v247
	v_mov_b32_e32 v66, v248
	v_mov_b32_e32 v67, v249
	v_mov_b32_e32 v60, v250
	v_mov_b32_e32 v61, v251
	v_mov_b32_e32 v62, v252
	v_mov_b32_e32 v63, v253
	s_cmp_lt_u32 s16, 3
	s_cbranch_scc0 .Lssm_nopf
	v_add_u32_e32 v172, 8, v154
	v_lshlrev_b32_e32 v168, 13, v172
	v_mov_b32_e32 v169, 0
	v_lshl_add_u64 v[168:169], v[100:101], 0, v[168:169]
	v_add_co_u32_e32 v170, vcc, 0x1000, v168
	s_nop 1
	v_addc_co_u32_e32 v171, vcc, 0, v169, vcc
	global_load_dwordx4 v[222:225], v[168:169], off
	global_load_dwordx4 v[226:229], v[168:169], off offset:1024
	global_load_dwordx4 v[230:233], v[168:169], off offset:2048
	global_load_dwordx4 v[234:237], v[168:169], off offset:3072
	global_load_dwordx4 v[238:241], v[170:171], off
	global_load_dwordx4 v[242:245], v[170:171], off offset:1024
	global_load_dwordx4 v[246:249], v[170:171], off offset:2048
	global_load_dwordx4 v[250:253], v[170:171], off offset:3072
.Lssm_nopf:
	v_mov_b32_e32 v15, 0
	v_cmp_lt_i32_e32 vcc, -1, v154
	v_mov_b32_e32 v14, v15
	v_mov_b32_e32 v13, v15
	v_mov_b32_e32 v12, v15
	v_mov_b32_e32 v11, v15
	v_mov_b32_e32 v10, v15
	v_mov_b32_e32 v9, v15
	v_mov_b32_e32 v8, v15
	v_mov_b32_e32 v7, v15
	v_mov_b32_e32 v6, v15
	v_mov_b32_e32 v5, v15
	v_mov_b32_e32 v4, v15
	v_mov_b32_e32 v3, v15
	v_mov_b32_e32 v2, v15
	v_mov_b32_e32 v1, v15
	v_mov_b32_e32 v0, v15
	s_and_saveexec_b64 s[12:13], vcc
	s_cbranch_execz .LBB0_210
	v_max_i32_e32 v0, 0, v153
	v_add_u32_e32 v155, 1, v0
	v_mov_b32_e32 v156, v123
	v_mov_b32_e32 v157, v152
	v_readfirstlane_b32 s14, v155
	v_mov_b32_e32 v0, 0
	v_mov_b32_e32 v1, v0
	v_mov_b32_e32 v2, v0
	v_mov_b32_e32 v3, v0
	v_mov_b32_e32 v4, v0
	v_mov_b32_e32 v5, v0
	v_mov_b32_e32 v6, v0
	v_mov_b32_e32 v7, v0
	v_mov_b32_e32 v8, v0
	v_mov_b32_e32 v9, v0
	v_mov_b32_e32 v10, v0
	v_mov_b32_e32 v11, v0
	v_mov_b32_e32 v12, v0
	v_mov_b32_e32 v13, v0
	v_mov_b32_e32 v14, v0
	v_mov_b32_e32 v15, v0
	s_mov_b32 s15, s14
	ds_read_b128 v[158:161], v157
	ds_read_b128 v[164:167], v156
	v_add_u32_e32 v157, 0xfffffe00, v157
	v_add_u32_e32 v156, 32, v156
	s_sub_u32 s15, s15, 1
	s_cmp_eq_u32 s15, 0
	s_cbranch_scc1 .Lssm_t0
	ds_read_b128 v[168:171], v157
	ds_read_b128 v[172:175], v156
	v_add_u32_e32 v157, 0xfffffe00, v157
	v_add_u32_e32 v156, 32, v156
	s_sub_u32 s15, s15, 1
	s_cmp_eq_u32 s15, 0
	s_cbranch_scc1 .Lssm_t0
	ds_read_b128 v[176:179], v157
	ds_read_b128 v[180:183], v156
	v_add_u32_e32 v157, 0xfffffe00, v157
	v_add_u32_e32 v156, 32, v156
	s_sub_u32 s15, s15, 1
